# attention loop: K/V pointer updates moved from the loop tail into the post-QK MFMA wait window
# speedup vs baseline: 1.0287x; 1.0004x over previous
; template <bool NA> ...
;     ...
;     for (int j = 0; j < ntiles; ++j) {
;         const int cur = j & 1;
;         if (j + 1 < ntiles) { const int t0 = (j + 1) < 4 ? SEQ + 64 * (j + 1) : loc_base + 64 * (j + 1 - 4);
;             kreg = *(const u32x4*)(PB + (size_t)(t0 + srow) * INW + kcol + 8 * sch); vreg = *(const u32x4*)(VT + (size_t)srow * NTOK + t0 + 8 * sch); }
;     ...
;         __syncthreads();
.LBB0_304:
	s_add_i32 s2, s2, 1
	v_add_f32_e32 v142, v142, v50
	s_cmpk_lg_i32 s2, 0x104
	s_waitcnt lgkmcnt(0)
	s_barrier
	s_cbranch_scc0 .LBB0_294

; #define LAS __attribute__((address_space(3)))
; __device__ __forceinline__ float xor32_max(float v) { const auto rr = __builtin_amdgcn_permlane32_swap(__float_as_uint(v), __float_as_uint(v), false, false); return fmaxf(__uint_as_float(rr[0]), __uint_as_float(rr[1])); }
; template <bool NA> ...
;     ...
;             const LAS unsigned char* kb = lds + cur * KB; const LAS unsigned char* vb = lds + VOFF + cur * VB;
;             f32x16 p0, p1;
;             if (NA) {
; #pragma unroll
;                 for (int r = 0; r < 16; ++r) { p0[r] = 0.f; p1[r] = 0.f; }
;             } else { p0 = negm; p1 = negm; }
;             bf16x8 kf[8], vfr[8];
; #pragma unroll
;             for (int s = 0; s < 4; ++s) {
;                 kf[2 * s] = *(const LAS bf16x8*)(kb + q * 144 + (16 * s + 8 * h) * 2);
;                 kf[2 * s + 1] = *(const LAS bf16x8*)(kb + (q + 32) * 144 + (16 * s + 8 * h) * 2);
;             }
; #pragma unroll
;             for (int s = 0; s < 4; ++s) {
;                 vfr[2 * s] = *(const LAS bf16x8*)(vb + q * 144 + 32 * s + 16 * h);
;                 vfr[2 * s + 1] = *(const LAS bf16x8*)(vb + (q + 32) * 144 + 32 * s + 16 * h);
;             }
;             __builtin_amdgcn_sched_barrier(0);
;             __builtin_amdgcn_s_setprio(1);
; #pragma unroll
;             for (int s = 0; s < 4; ++s) {
;                 p0 = __builtin_amdgcn_mfma_f32_32x32x16_bf16(kf[2 * s], qb[s], p0, 0, 0, 0);
;                 p1 = __builtin_amdgcn_mfma_f32_32x32x16_bf16(kf[2 * s + 1], qb[s], p1, 0, 0, 0);
;             }
;             __builtin_amdgcn_s_setprio(0);
;     ...
;             float mx = fmaxf(fmaxf(p0[0], p1[0]), p0[1]), mx2 = fmaxf(fmaxf(p1[1], p0[2]), p1[2]);
; #pragma unroll
;             for (int r = 3; r < 15; r += 3) { mx = fmaxf(fmaxf(mx, p0[r]), p1[r]); mx2 = fmaxf(fmaxf(mx2, p0[r + 1]), p1[r + 1]); mx = fmaxf(fmaxf(mx, p0[r + 2]), p1[r + 2]); }
;             mx = fmaxf(fmaxf(mx, mx2), fmaxf(p0[15], p1[15]));
;             mx = xor32_max(mx);
.LBB0_307:
	s_and_b32 s20, s2, 1
	s_mul_i32 s22, s20, 0x2400
	v_add_u32_e32 v50, s22, v194
	ds_read_b128 v[66:69], v50
	ds_read_b128 v[144:147], v50 offset:32
	ds_read_b128 v[148:151], v50 offset:4608
	ds_read_b128 v[188:191], v50 offset:4640
	ds_read_b128 v[196:199], v50 offset:64
	ds_read_b128 v[218:221], v50 offset:96
	ds_read_b128 v[222:225], v50 offset:4672
	ds_read_b128 v[226:229], v50 offset:4704
	ds_read_b128 v[134:137], v50 offset:18432
	ds_read_b128 v[126:129], v50 offset:18464
	ds_read_b128 v[130:133], v50 offset:23040
	ds_read_b128 v[122:125], v50 offset:23072
	ds_read_b128 v[118:121], v50 offset:18496
	ds_read_b128 v[90:93], v50 offset:18528
	ds_read_b128 v[114:117], v50 offset:23104
	ds_read_b128 v[94:97], v50 offset:23136
	s_setprio 1
	s_waitcnt lgkmcnt(14)
	v_mfma_f32_32x32x16_bf16 v[50:65], v[66:69], v[98:101], v[2:17]
	v_mfma_f32_32x32x16_bf16 v[50:65], v[144:147], v[102:105], v[50:65]
	s_waitcnt lgkmcnt(13)
	v_mfma_f32_32x32x16_bf16 v[66:81], v[148:151], v[98:101], v[2:17]
	s_waitcnt lgkmcnt(12)
	v_mfma_f32_32x32x16_bf16 v[66:81], v[188:191], v[102:105], v[66:81]
	s_waitcnt lgkmcnt(11)
	v_mfma_f32_32x32x16_bf16 v[50:65], v[196:199], v[106:109], v[50:65]
	s_waitcnt lgkmcnt(9)
	v_mfma_f32_32x32x16_bf16 v[66:81], v[222:225], v[106:109], v[66:81]
	v_mfma_f32_32x32x16_bf16 v[50:65], v[218:221], v[110:113], v[50:65]
	s_waitcnt lgkmcnt(8)
	v_mfma_f32_32x32x16_bf16 v[66:81], v[226:229], v[110:113], v[66:81]
	s_setprio 0
	s_mov_b64 s[22:23], 0xd8000
	v_lshl_add_u64 v[138:139], v[138:139], 0, s[22:23]
	v_lshl_add_u64 v[140:141], v[140:141], 0, s[10:11]
	s_nop 7
	v_max3_f32 v143, v50, v66, v51
	v_max3_f32 v143, v143, v53, v69
	v_max3_f32 v143, v143, v55, v71
	v_max3_f32 v143, v143, v56, v72
	v_max3_f32 v144, v67, v52, v68
	v_max3_f32 v143, v143, v58, v74
	v_max3_f32 v144, v144, v54, v70
	v_max3_f32 v143, v143, v59, v75
	v_max3_f32 v144, v144, v57, v73
	v_max3_f32 v143, v143, v61, v77
	v_max3_f32 v144, v144, v60, v76
	v_max3_f32 v143, v143, v62, v78
	v_max3_f32 v144, v144, v63, v79
	v_max3_f32 v143, v143, v64, v80
	v_max_f32_e32 v145, v65, v81
	v_max3_f32 v143, v143, v144, v145
	v_mov_b32_e32 v144, v143
	s_nop 1
	v_permlane32_swap_b32_e32 v143, v144
	v_max_f32_e32 v143, v143, v144
	v_cmp_lt_f32_e32 vcc, 0, v143
	s_cbranch_vccz .LBB0_309
	s_nop 0
	v_cndmask_b32_e32 v4, 0, v143, vcc
	v_exp_f32_e64 v6, -v4
	v_add_f32_e32 v183, v183, v4
	v_xor_b32_e32 v2, 0x80000000, v183
	v_pk_add_f32 v[50:51], v[50:51], v[4:5] op_sel_hi:[1,0] neg_lo:[0,1] neg_hi:[0,1]
	v_pk_add_f32 v[66:67], v[66:67], v[4:5] op_sel_hi:[1,0] neg_lo:[0,1] neg_hi:[0,1]
	v_pk_add_f32 v[52:53], v[52:53], v[4:5] op_sel_hi:[1,0] neg_lo:[0,1] neg_hi:[0,1]
	v_pk_add_f32 v[68:69], v[68:69], v[4:5] op_sel_hi:[1,0] neg_lo:[0,1] neg_hi:[0,1]
	v_pk_add_f32 v[54:55], v[54:55], v[4:5] op_sel_hi:[1,0] neg_lo:[0,1] neg_hi:[0,1]
	v_pk_add_f32 v[70:71], v[70:71], v[4:5] op_sel_hi:[1,0] neg_lo:[0,1] neg_hi:[0,1]
	v_pk_add_f32 v[56:57], v[56:57], v[4:5] op_sel_hi:[1,0] neg_lo:[0,1] neg_hi:[0,1]
	v_pk_add_f32 v[72:73], v[72:73], v[4:5] op_sel_hi:[1,0] neg_lo:[0,1] neg_hi:[0,1]
	v_pk_add_f32 v[58:59], v[58:59], v[4:5] op_sel_hi:[1,0] neg_lo:[0,1] neg_hi:[0,1]
	v_pk_add_f32 v[74:75], v[74:75], v[4:5] op_sel_hi:[1,0] neg_lo:[0,1] neg_hi:[0,1]
	v_pk_add_f32 v[60:61], v[60:61], v[4:5] op_sel_hi:[1,0] neg_lo:[0,1] neg_hi:[0,1]
	v_pk_add_f32 v[76:77], v[76:77], v[4:5] op_sel_hi:[1,0] neg_lo:[0,1] neg_hi:[0,1]
	v_pk_add_f32 v[62:63], v[62:63], v[4:5] op_sel_hi:[1,0] neg_lo:[0,1] neg_hi:[0,1]
	v_pk_add_f32 v[78:79], v[78:79], v[4:5] op_sel_hi:[1,0] neg_lo:[0,1] neg_hi:[0,1]
	v_pk_mul_f32 v[48:49], v[48:49], v[6:7] op_sel_hi:[1,0]
	v_pk_mul_f32 v[46:47], v[46:47], v[6:7] op_sel_hi:[1,0]
	v_pk_mul_f32 v[44:45], v[44:45], v[6:7] op_sel_hi:[1,0]
	v_pk_mul_f32 v[42:43], v[42:43], v[6:7] op_sel_hi:[1,0]
	v_pk_mul_f32 v[40:41], v[40:41], v[6:7] op_sel_hi:[1,0]
	v_pk_mul_f32 v[38:39], v[38:39], v[6:7] op_sel_hi:[1,0]
	v_pk_mul_f32 v[36:37], v[36:37], v[6:7] op_sel_hi:[1,0]
	v_pk_mul_f32 v[34:35], v[34:35], v[6:7] op_sel_hi:[1,0]
	v_pk_mul_f32 v[32:33], v[32:33], v[6:7] op_sel_hi:[1,0]
	v_pk_mul_f32 v[30:31], v[30:31], v[6:7] op_sel_hi:[1,0]
	v_pk_mul_f32 v[28:29], v[28:29], v[6:7] op_sel_hi:[1,0]
	v_pk_mul_f32 v[26:27], v[26:27], v[6:7] op_sel_hi:[1,0]
	v_pk_mul_f32 v[24:25], v[24:25], v[6:7] op_sel_hi:[1,0]
	v_pk_mul_f32 v[22:23], v[22:23], v[6:7] op_sel_hi:[1,0]
	v_pk_mul_f32 v[20:21], v[20:21], v[6:7] op_sel_hi:[1,0]
	v_pk_mul_f32 v[18:19], v[18:19], v[6:7] op_sel_hi:[1,0]
	v_pk_add_f32 v[64:65], v[64:65], v[4:5] op_sel_hi:[1,0] neg_lo:[0,1] neg_hi:[0,1]
	v_pk_add_f32 v[80:81], v[80:81], v[4:5] op_sel_hi:[1,0] neg_lo:[0,1] neg_hi:[0,1]
	v_mul_f32_e32 v142, v142, v6
	v_mov_b32_e32 v3, v2
	v_mov_b32_e32 v4, v2
	v_mov_b32_e32 v5, v2
	v_mov_b32_e32 v6, v2
	v_mov_b32_e32 v7, v2
	v_mov_b32_e32 v8, v2
	v_mov_b32_e32 v9, v2
	v_mov_b32_e32 v10, v2
	v_mov_b32_e32 v11, v2
	v_mov_b32_e32 v12, v2
	v_mov_b32_e32 v13, v2
	v_mov_b32_e32 v14, v2
	v_mov_b32_e32 v15, v2
	v_mov_b32_e32 v16, v2
	v_mov_b32_e32 v17, v2
